# phase 0 adaLN item: silu(c) staging loop unrolled, 20 loads in flight (prologue de-serialisation)
# speedup vs baseline: 1.0089x; 1.0089x over previous
; DI float siluf(float x) { return x * __builtin_amdgcn_rcpf(1.f + __expf(-x)); }
; DI void adaln_item(const P& p, int a, unsigned char* smem) {
;     ...
;     for (int e = tid; e < 5 * 2048; e += 512) { const int r = e >> 11, k = e & 2047; const float v = r < 4 ? p.c[r * 2048 + k] : p.c_ctx[k]; sc[e] = siluf(v); }
;     __syncthreads();
.LBB0_32:
	v_mov_b32_e32 v78, v166
	s_nop 0
	v_cmp_lt_i32_e32 vcc, s39, v78
	v_lshlrev_b32_e32 v177, 2, v78
	s_and_saveexec_b64 s[26:27], vcc
	s_xor_b64 s[26:27], exec, s[26:27]
	v_lshlrev_b32_e32 v177, 2, v78
	s_andn2_saveexec_b64 s[26:27], s[26:27]
	s_cbranch_execz .LBB0_38
	v_add_u32_e32 v2, s62, v177
	s_add_u32 s28, s16, 0x0
	s_addc_u32 s29, s17, 0
	global_load_dword v20, v177, s[28:29]
	s_add_u32 s28, s16, 0x800
	s_addc_u32 s29, s17, 0
	global_load_dword v21, v177, s[28:29]
	s_add_u32 s28, s16, 0x1000
	s_addc_u32 s29, s17, 0
	global_load_dword v22, v177, s[28:29]
	s_add_u32 s28, s16, 0x1800
	s_addc_u32 s29, s17, 0
	global_load_dword v23, v177, s[28:29]
	s_add_u32 s28, s16, 0x2000
	s_addc_u32 s29, s17, 0
	global_load_dword v24, v177, s[28:29]
	s_add_u32 s28, s16, 0x2800
	s_addc_u32 s29, s17, 0
	global_load_dword v25, v177, s[28:29]
	s_add_u32 s28, s16, 0x3000
	s_addc_u32 s29, s17, 0
	global_load_dword v26, v177, s[28:29]
	s_add_u32 s28, s16, 0x3800
	s_addc_u32 s29, s17, 0
	global_load_dword v27, v177, s[28:29]
	s_add_u32 s28, s16, 0x4000
	s_addc_u32 s29, s17, 0
	global_load_dword v28, v177, s[28:29]
	s_add_u32 s28, s16, 0x4800
	s_addc_u32 s29, s17, 0
	global_load_dword v29, v177, s[28:29]
	s_add_u32 s28, s16, 0x5000
	s_addc_u32 s29, s17, 0
	global_load_dword v30, v177, s[28:29]
	s_add_u32 s28, s16, 0x5800
	s_addc_u32 s29, s17, 0
	global_load_dword v31, v177, s[28:29]
	s_add_u32 s28, s16, 0x6000
	s_addc_u32 s29, s17, 0
	global_load_dword v32, v177, s[28:29]
	s_add_u32 s28, s16, 0x6800
	s_addc_u32 s29, s17, 0
	global_load_dword v33, v177, s[28:29]
	s_add_u32 s28, s16, 0x7000
	s_addc_u32 s29, s17, 0
	global_load_dword v34, v177, s[28:29]
	s_add_u32 s28, s16, 0x7800
	s_addc_u32 s29, s17, 0
	global_load_dword v35, v177, s[28:29]
	s_add_u32 s28, s8, 0x0
	s_addc_u32 s29, s9, 0
	global_load_dword v36, v177, s[28:29]
	s_add_u32 s28, s8, 0x800
	s_addc_u32 s29, s9, 0
	global_load_dword v37, v177, s[28:29]
	s_add_u32 s28, s8, 0x1000
	s_addc_u32 s29, s9, 0
	global_load_dword v38, v177, s[28:29]
	s_add_u32 s28, s8, 0x1800
	s_addc_u32 s29, s9, 0
	global_load_dword v39, v177, s[28:29]
	s_waitcnt vmcnt(18)
	v_mul_f32_e32 v44, 0xbfb8aa3b, v20
	v_mul_f32_e32 v45, 0xbfb8aa3b, v21
	v_exp_f32_e32 v44, v44
	v_exp_f32_e32 v45, v45
	v_add_f32_e32 v44, 1.0, v44
	v_add_f32_e32 v45, 1.0, v45
	v_rcp_f32_e32 v44, v44
	v_rcp_f32_e32 v45, v45
	v_mul_f32_e32 v20, v20, v44
	v_mul_f32_e32 v21, v21, v45
	ds_write_b32 v2, v20 offset:0
	ds_write_b32 v2, v21 offset:2048
	s_waitcnt vmcnt(16)
	v_mul_f32_e32 v44, 0xbfb8aa3b, v22
	v_mul_f32_e32 v45, 0xbfb8aa3b, v23
	v_exp_f32_e32 v44, v44
	v_exp_f32_e32 v45, v45
	v_add_f32_e32 v44, 1.0, v44
	v_add_f32_e32 v45, 1.0, v45
	v_rcp_f32_e32 v44, v44
	v_rcp_f32_e32 v45, v45
	v_mul_f32_e32 v22, v22, v44
	v_mul_f32_e32 v23, v23, v45
	ds_write_b32 v2, v22 offset:4096
	ds_write_b32 v2, v23 offset:6144
	s_waitcnt vmcnt(14)
	v_mul_f32_e32 v44, 0xbfb8aa3b, v24
	v_mul_f32_e32 v45, 0xbfb8aa3b, v25
	v_exp_f32_e32 v44, v44
	v_exp_f32_e32 v45, v45
	v_add_f32_e32 v44, 1.0, v44
	v_add_f32_e32 v45, 1.0, v45
	v_rcp_f32_e32 v44, v44
	v_rcp_f32_e32 v45, v45
	v_mul_f32_e32 v24, v24, v44
	v_mul_f32_e32 v25, v25, v45
	ds_write_b32 v2, v24 offset:8192
	ds_write_b32 v2, v25 offset:10240
	s_waitcnt vmcnt(12)
	v_mul_f32_e32 v44, 0xbfb8aa3b, v26
	v_mul_f32_e32 v45, 0xbfb8aa3b, v27
	v_exp_f32_e32 v44, v44
	v_exp_f32_e32 v45, v45
	v_add_f32_e32 v44, 1.0, v44
	v_add_f32_e32 v45, 1.0, v45
	v_rcp_f32_e32 v44, v44
	v_rcp_f32_e32 v45, v45
	v_mul_f32_e32 v26, v26, v44
	v_mul_f32_e32 v27, v27, v45
	ds_write_b32 v2, v26 offset:12288
	ds_write_b32 v2, v27 offset:14336
	s_waitcnt vmcnt(10)
	v_mul_f32_e32 v44, 0xbfb8aa3b, v28
	v_mul_f32_e32 v45, 0xbfb8aa3b, v29
	v_exp_f32_e32 v44, v44
	v_exp_f32_e32 v45, v45
	v_add_f32_e32 v44, 1.0, v44
	v_add_f32_e32 v45, 1.0, v45
	v_rcp_f32_e32 v44, v44
	v_rcp_f32_e32 v45, v45
	v_mul_f32_e32 v28, v28, v44
	v_mul_f32_e32 v29, v29, v45
	ds_write_b32 v2, v28 offset:16384
	ds_write_b32 v2, v29 offset:18432
	s_waitcnt vmcnt(8)
	v_mul_f32_e32 v44, 0xbfb8aa3b, v30
	v_mul_f32_e32 v45, 0xbfb8aa3b, v31
	v_exp_f32_e32 v44, v44
	v_exp_f32_e32 v45, v45
	v_add_f32_e32 v44, 1.0, v44
	v_add_f32_e32 v45, 1.0, v45
	v_rcp_f32_e32 v44, v44
	v_rcp_f32_e32 v45, v45
	v_mul_f32_e32 v30, v30, v44
	v_mul_f32_e32 v31, v31, v45
	ds_write_b32 v2, v30 offset:20480
	ds_write_b32 v2, v31 offset:22528
	s_waitcnt vmcnt(6)
	v_mul_f32_e32 v44, 0xbfb8aa3b, v32
	v_mul_f32_e32 v45, 0xbfb8aa3b, v33
	v_exp_f32_e32 v44, v44
	v_exp_f32_e32 v45, v45
	v_add_f32_e32 v44, 1.0, v44
	v_add_f32_e32 v45, 1.0, v45
	v_rcp_f32_e32 v44, v44
	v_rcp_f32_e32 v45, v45
	v_mul_f32_e32 v32, v32, v44
	v_mul_f32_e32 v33, v33, v45
	ds_write_b32 v2, v32 offset:24576
	ds_write_b32 v2, v33 offset:26624
	s_waitcnt vmcnt(4)
	v_mul_f32_e32 v44, 0xbfb8aa3b, v34
	v_mul_f32_e32 v45, 0xbfb8aa3b, v35
	v_exp_f32_e32 v44, v44
	v_exp_f32_e32 v45, v45
	v_add_f32_e32 v44, 1.0, v44
	v_add_f32_e32 v45, 1.0, v45
	v_rcp_f32_e32 v44, v44
	v_rcp_f32_e32 v45, v45
	v_mul_f32_e32 v34, v34, v44
	v_mul_f32_e32 v35, v35, v45
	ds_write_b32 v2, v34 offset:28672
	ds_write_b32 v2, v35 offset:30720
	s_waitcnt vmcnt(2)
	v_mul_f32_e32 v44, 0xbfb8aa3b, v36
	v_mul_f32_e32 v45, 0xbfb8aa3b, v37
	v_exp_f32_e32 v44, v44
	v_exp_f32_e32 v45, v45
	v_add_f32_e32 v44, 1.0, v44
	v_add_f32_e32 v45, 1.0, v45
	v_rcp_f32_e32 v44, v44
	v_rcp_f32_e32 v45, v45
	v_mul_f32_e32 v36, v36, v44
	v_mul_f32_e32 v37, v37, v45
	ds_write_b32 v2, v36 offset:32768
	ds_write_b32 v2, v37 offset:34816
	s_waitcnt vmcnt(0)
	v_mul_f32_e32 v44, 0xbfb8aa3b, v38
	v_mul_f32_e32 v45, 0xbfb8aa3b, v39
	v_exp_f32_e32 v44, v44
	v_exp_f32_e32 v45, v45
	v_add_f32_e32 v44, 1.0, v44
	v_add_f32_e32 v45, 1.0, v45
	v_rcp_f32_e32 v44, v44
	v_rcp_f32_e32 v45, v45
	v_mul_f32_e32 v38, v38, v44
	v_mul_f32_e32 v39, v39, v45
	ds_write_b32 v2, v38 offset:36864
	ds_write_b32 v2, v39 offset:38912
